# conv phase: xor-2 and xor-1 reduction hops via quad_perm DPP adds instead of ds_bpermute round trips
# baseline (speedup 1.0000x reference)
; __device__ __forceinline__ unsigned cvt_pk_bf16(float lo, float hi) { unsigned r; asm volatile("v_cvt_pk_bf16_f32 %0, %1, %2" : "=v"(r) : "v"(lo), "v"(hi)); return r; }
; __device__ __forceinline__ float bflo(unsigned w) { return __uint_as_float(w << 16); }
; __device__ __forceinline__ void conv_phase(const Params& p, int l, int rbase) {
;     ...
;     for (; t < tend; t += tstep) {
;         u32x2 gb[4], gc0[4], hi0[4], gc1[4], hi1[4], gc2[4], hi2[4];
; #pragma unroll
;         for (int i = 0; i < 4; ++i) { gb[i] = ngb[i]; gc0[i] = ngc0[i]; hi0[i] = nhi0[i]; gc1[i] = ngc1[i]; hi1[i] = nhi1[i]; gc2[i] = ngc2[i]; hi2[i] = nhi2[i]; }
;         { const int tn = t + tstep; if (tn < tend) CONV_LOAD(tn); }
;         f32x4 cw0[4], cw1[4], cw2[4], g2[4];
; #pragma unroll
;         for (int i = 0; i < 4; ++i) { const int col = i * 256 + lane * 4;
;             cw0[i] = *(const f32x4*)(cw + col); cw1[i] = *(const f32x4*)(cw + 1024 + col); cw2[i] = *(const f32x4*)(cw + 2048 + col); g2[i] = *(const f32x4*)(gain + 1024 + col); }
; #pragma unroll
;         for (int i = 0; i < 4; ++i) {
;             const int col = i * 256 + lane * 4;
;             f32x4 c0, c1, c2, gbv;
;             c0[0] = bflo(gc0[i].x) * bflo(hi0[i].x); c0[1] = bfhi(gc0[i].x) * bfhi(hi0[i].x); c0[2] = bflo(gc0[i].y) * bflo(hi0[i].y); c0[3] = bfhi(gc0[i].y) * bfhi(hi0[i].y);
;             c1[0] = bflo(gc1[i].x) * bflo(hi1[i].x); c1[1] = bfhi(gc1[i].x) * bfhi(hi1[i].x); c1[2] = bflo(gc1[i].y) * bflo(hi1[i].y); c1[3] = bfhi(gc1[i].y) * bfhi(hi1[i].y);
;             c2[0] = bflo(gc2[i].x) * bflo(hi2[i].x); c2[1] = bfhi(gc2[i].x) * bfhi(hi2[i].x); c2[2] = bflo(gc2[i].y) * bflo(hi2[i].y); c2[3] = bfhi(gc2[i].y) * bfhi(hi2[i].y);
;             gbv[0] = bflo(gb[i].x); gbv[1] = bfhi(gb[i].x); gbv[2] = bflo(gb[i].y); gbv[3] = bfhi(gb[i].y);
;             f32x4 y = gbv * (cw0[i] * c2 + cw1[i] * c1 + cw2[i] * c0);
;             float s2 = (y[0] * y[0] + y[1] * y[1]) + (y[2] * y[2] + y[3] * y[3]);
; #pragma unroll
;             for (int sft = 16; sft >= 1; sft >>= 1) s2 += __shfl_xor(s2, sft);
;             const float rs2 = rsqrtf(s2 * (1.0f / 128.0f) + 1e-6f);
;             y = y * rs2 * g2[i];
;             u32x2 wy; wy.x = cvt_pk_bf16(y[0], y[1]); wy.y = cvt_pk_bf16(y[2], y[3]);
;             *(u32x2*)(mixed + pg8::tiled_off(t, 1024 + col, DM / 64)) = wy;
.LBB0_276:
	s_or_b64 exec, exec, s[10:11]
	global_load_dwordx4 v[208:211], v[50:51], off
	global_load_dwordx4 v[212:215], v[52:53], off
	global_load_dwordx4 v[216:219], v[54:55], off
	global_load_dwordx4 v[228:231], v[56:57], off
	global_load_dwordx4 v[40:43], v[50:51], off offset:1024
	global_load_dwordx4 v[44:47], v[58:59], off
	global_load_dwordx4 v[36:39], v[60:61], off
	global_load_dwordx4 v[32:35], v[62:63], off
	global_load_dwordx4 v[20:23], v[50:51], off offset:2048
	global_load_dwordx4 v[28:31], v[64:65], off
	global_load_dwordx4 v[24:27], v[66:67], off
	global_load_dwordx4 v[16:19], v[68:69], off
	global_load_dwordx4 v[8:11], v[50:51], off offset:3072
	global_load_dwordx4 v[12:15], v[70:71], off
	global_load_dwordx4 v[4:7], v[72:73], off
	global_load_dwordx4 v[0:3], v[74:75], off
	v_lshlrev_b32_e32 v232, 16, v192
	v_and_b32_e32 v233, 0xffff0000, v192
	v_lshlrev_b32_e32 v234, 16, v190
	v_and_b32_e32 v235, 0xffff0000, v190
	v_lshlrev_b32_e32 v192, 16, v193
	v_and_b32_e32 v193, 0xffff0000, v193
	v_lshlrev_b32_e32 v190, 16, v191
	v_and_b32_e32 v191, 0xffff0000, v191
	v_pk_mul_f32 v[232:233], v[234:235], v[232:233]
	v_pk_mul_f32 v[190:191], v[190:191], v[192:193]
	v_lshlrev_b32_e32 v192, 16, v188
	v_and_b32_e32 v193, 0xffff0000, v188
	v_lshlrev_b32_e32 v234, 16, v184
	v_and_b32_e32 v235, 0xffff0000, v184
	v_lshlrev_b32_e32 v188, 16, v189
	v_and_b32_e32 v189, 0xffff0000, v189
	v_lshlrev_b32_e32 v184, 16, v185
	v_and_b32_e32 v185, 0xffff0000, v185
	v_pk_mul_f32 v[192:193], v[234:235], v[192:193]
	v_pk_mul_f32 v[184:185], v[184:185], v[188:189]
	v_lshlrev_b32_e32 v188, 16, v186
	v_and_b32_e32 v189, 0xffff0000, v186
	v_lshlrev_b32_e32 v234, 16, v182
	v_and_b32_e32 v235, 0xffff0000, v182
	v_lshlrev_b32_e32 v186, 16, v187
	v_and_b32_e32 v187, 0xffff0000, v187
	v_lshlrev_b32_e32 v182, 16, v183
	v_and_b32_e32 v183, 0xffff0000, v183
	v_pk_mul_f32 v[188:189], v[234:235], v[188:189]
	v_pk_mul_f32 v[182:183], v[182:183], v[186:187]
	v_ashrrev_i32_e32 v152, 2, v166
	v_lshlrev_b32_e32 v186, 16, v180
	v_and_b32_e32 v187, 0xffff0000, v180
	v_lshlrev_b32_e32 v180, 16, v181
	v_and_b32_e32 v181, 0xffff0000, v181
	v_and_b32_e32 v207, 0xffffffe0, v152
	v_lshrrev_b32_e32 v152, 3, v166
	s_and_b64 s[0:1], exec, s[0:1]
	v_and_or_b32 v152, v152, 14, v194
	v_lshrrev_b32_e32 v167, 4, v205
	s_or_b64 s[8:9], s[0:1], s[8:9]
	v_and_or_b32 v166, v205, s22, v195
	v_lshlrev_b32_e32 v152, 10, v152
	v_and_b32_e32 v167, 32, v167
	v_readlane_b32 s0, v252, 53
	v_bitop3_b32 v152, v166, v152, v167 bitop3:0xde
	v_readlane_b32 s1, v252, 54
	v_add_u32_e32 v205, s16, v205
	s_waitcnt vmcnt(0)
	v_pk_mul_f32 v[184:185], v[184:185], v[214:215]
	v_pk_mul_f32 v[192:193], v[192:193], v[212:213]
	v_pk_fma_f32 v[182:183], v[182:183], v[210:211], v[184:185]
	v_pk_fma_f32 v[188:189], v[188:189], v[208:209], v[192:193]
	v_pk_fma_f32 v[182:183], v[190:191], v[218:219], v[182:183]
	v_pk_fma_f32 v[184:185], v[232:233], v[216:217], v[188:189]
	v_pk_mul_f32 v[180:181], v[182:183], v[180:181]
	v_pk_mul_f32 v[184:185], v[184:185], v[186:187]
	v_pk_mul_f32 v[182:183], v[180:181], v[180:181]
	v_pk_mul_f32 v[186:187], v[184:185], v[184:185]
	v_lshl_add_u64 v[166:167], s[0:1], 0, v[152:153]
	v_pk_mov_b32 v[188:189], v[186:187], v[182:183] op_sel:[1,0]
	v_mov_b32_e32 v187, v183
	v_pk_add_f32 v[182:183], v[188:189], v[186:187]
	s_mov_b32 s0, 0x800000
	v_add_f32_e32 v152, v182, v183
	ds_bpermute_b32 v182, v196, v152
	v_mov_b64_e32 v[186:187], v[98:99]
	v_mov_b64_e32 v[188:189], v[84:85]
	v_mov_b64_e32 v[190:191], v[80:81]
	v_mov_b64_e32 v[192:193], v[78:79]
	s_waitcnt lgkmcnt(0)
	v_add_f32_e32 v152, v152, v182
	ds_bpermute_b32 v182, v197, v152
	s_waitcnt lgkmcnt(0)
	v_add_f32_e32 v152, v152, v182
	ds_bpermute_b32 v182, v198, v152
	s_waitcnt lgkmcnt(0)
	v_add_f32_e32 v152, v152, v182
	s_nop 1
	v_add_f32_dpp v152, v152, v152 quad_perm:[2,3,0,1] row_mask:0xf bank_mask:0xf
	s_nop 1
	v_add_f32_dpp v152, v152, v152 quad_perm:[1,0,3,2] row_mask:0xf bank_mask:0xf
	v_fmamk_f32 v152, v152, 0x3c000000, v224
	v_cmp_gt_f32_e32 vcc, s0, v152
	v_mul_f32_e32 v182, 0x4b800000, v152
	s_nop 0
	v_cndmask_b32_e32 v152, v152, v182, vcc
	v_rsq_f32_e32 v152, v152
	s_nop 0
	v_mul_f32_e32 v182, 0x45800000, v152
	v_cndmask_b32_e32 v152, v152, v182, vcc
	v_pk_mul_f32 v[182:183], v[184:185], v[152:153] op_sel_hi:[1,0]
	v_pk_mul_f32 v[180:181], v[180:181], v[152:153] op_sel_hi:[1,0]
	v_pk_mul_f32 v[182:183], v[228:229], v[182:183]
	v_pk_mul_f32 v[180:181], v[230:231], v[180:181]
	v_cvt_pk_bf16_f32 v182, v182, v183
	v_mov_b64_e32 v[184:185], v[86:87]
	v_cvt_pk_bf16_f32 v183, v180, v181
	v_or_b32_e32 v180, v207, v201
	v_ashrrev_i32_e32 v181, 31, v180
	v_lshlrev_b64 v[180:181], 14, v[180:181]
	v_lshl_add_u64 v[180:181], v[166:167], 0, v[180:181]
	global_store_dwordx2 v[180:181], v[182:183], off
	v_lshlrev_b32_e32 v180, 16, v178
	v_and_b32_e32 v181, 0xffff0000, v178
	v_lshlrev_b32_e32 v182, 16, v176
	v_and_b32_e32 v183, 0xffff0000, v176
	v_lshlrev_b32_e32 v178, 16, v179
	v_and_b32_e32 v179, 0xffff0000, v179
	v_lshlrev_b32_e32 v176, 16, v177
	v_and_b32_e32 v177, 0xffff0000, v177
	v_pk_mul_f32 v[180:181], v[182:183], v[180:181]
	v_pk_mul_f32 v[176:177], v[176:177], v[178:179]
	v_lshlrev_b32_e32 v178, 16, v174
	v_and_b32_e32 v179, 0xffff0000, v174
	v_lshlrev_b32_e32 v182, 16, v172
	v_and_b32_e32 v183, 0xffff0000, v172
	v_lshlrev_b32_e32 v174, 16, v175
	v_and_b32_e32 v175, 0xffff0000, v175
	v_lshlrev_b32_e32 v172, 16, v173
	v_and_b32_e32 v173, 0xffff0000, v173
	v_pk_mul_f32 v[178:179], v[182:183], v[178:179]
	v_pk_mul_f32 v[172:173], v[172:173], v[174:175]
	v_lshlrev_b32_e32 v174, 16, v170
	v_and_b32_e32 v175, 0xffff0000, v170
	v_lshlrev_b32_e32 v182, 16, v168
	v_and_b32_e32 v183, 0xffff0000, v168
	v_lshlrev_b32_e32 v170, 16, v171
	v_and_b32_e32 v171, 0xffff0000, v171
	v_lshlrev_b32_e32 v168, 16, v169
	v_and_b32_e32 v169, 0xffff0000, v169
	v_pk_mul_f32 v[174:175], v[182:183], v[174:175]
	v_pk_mul_f32 v[168:169], v[168:169], v[170:171]
	v_pk_mul_f32 v[46:47], v[172:173], v[46:47]
	v_pk_mul_f32 v[44:45], v[178:179], v[44:45]
	v_pk_fma_f32 v[42:43], v[168:169], v[42:43], v[46:47]
	v_pk_fma_f32 v[40:41], v[174:175], v[40:41], v[44:45]
	v_lshlrev_b32_e32 v170, 16, v164
	v_and_b32_e32 v171, 0xffff0000, v164
	v_lshlrev_b32_e32 v164, 16, v165
	v_and_b32_e32 v165, 0xffff0000, v165
	v_pk_fma_f32 v[38:39], v[176:177], v[38:39], v[42:43]
	v_pk_fma_f32 v[36:37], v[180:181], v[36:37], v[40:41]
	v_pk_mul_f32 v[38:39], v[38:39], v[164:165]
	v_pk_mul_f32 v[36:37], v[36:37], v[170:171]
	v_pk_mul_f32 v[40:41], v[38:39], v[38:39]
	v_pk_mul_f32 v[42:43], v[36:37], v[36:37]
	v_lshlrev_b32_e32 v46, 16, v143
	v_pk_mov_b32 v[44:45], v[42:43], v[40:41] op_sel:[1,0]
	v_mov_b32_e32 v43, v41
	v_pk_add_f32 v[40:41], v[44:45], v[42:43]
	v_lshlrev_b32_e32 v42, 16, v144
	v_add_f32_e32 v40, v40, v41
	ds_bpermute_b32 v41, v196, v40
	v_and_b32_e32 v43, 0xffff0000, v144
	v_lshlrev_b32_e32 v44, 16, v145
	v_and_b32_e32 v45, 0xffff0000, v145
	v_and_b32_e32 v47, 0xffff0000, v143
	s_waitcnt lgkmcnt(0)
; __device__ __forceinline__ unsigned cvt_pk_bf16(float lo, float hi) { unsigned r; asm volatile("v_cvt_pk_bf16_f32 %0, %1, %2" : "=v"(r) : "v"(lo), "v"(hi)); return r; }
; __device__ __forceinline__ float bflo(unsigned w) { return __uint_as_float(w << 16); }
; __device__ __forceinline__ float bfhi(unsigned w) { return __uint_as_float(w & 0xffff0000u); }
; __device__ __forceinline__ void conv_phase(const Params& p, int l, int rbase) {
;     ...
;         for (int i = 0; i < 4; ++i) { const int col = i * 256 + lane * 4;
;             cw0[i] = *(const f32x4*)(cw + col); cw1[i] = *(const f32x4*)(cw + 1024 + col); cw2[i] = *(const f32x4*)(cw + 2048 + col); g2[i] = *(const f32x4*)(gain + 1024 + col); }
; #pragma unroll
;         for (int i = 0; i < 4; ++i) {
;             const int col = i * 256 + lane * 4;
;             f32x4 c0, c1, c2, gbv;
;             c0[0] = bflo(gc0[i].x) * bflo(hi0[i].x); c0[1] = bfhi(gc0[i].x) * bfhi(hi0[i].x); c0[2] = bflo(gc0[i].y) * bflo(hi0[i].y); c0[3] = bfhi(gc0[i].y) * bfhi(hi0[i].y);
;             c1[0] = bflo(gc1[i].x) * bflo(hi1[i].x); c1[1] = bfhi(gc1[i].x) * bfhi(hi1[i].x); c1[2] = bflo(gc1[i].y) * bflo(hi1[i].y); c1[3] = bfhi(gc1[i].y) * bfhi(hi1[i].y);
;             c2[0] = bflo(gc2[i].x) * bflo(hi2[i].x); c2[1] = bfhi(gc2[i].x) * bfhi(hi2[i].x); c2[2] = bflo(gc2[i].y) * bflo(hi2[i].y); c2[3] = bfhi(gc2[i].y) * bfhi(hi2[i].y);
;             gbv[0] = bflo(gb[i].x); gbv[1] = bfhi(gb[i].x); gbv[2] = bflo(gb[i].y); gbv[3] = bfhi(gb[i].y);
;             f32x4 y = gbv * (cw0[i] * c2 + cw1[i] * c1 + cw2[i] * c0);
;             float s2 = (y[0] * y[0] + y[1] * y[1]) + (y[2] * y[2] + y[3] * y[3]);
; #pragma unroll
;             for (int sft = 16; sft >= 1; sft >>= 1) s2 += __shfl_xor(s2, sft);
;             const float rs2 = rsqrtf(s2 * (1.0f / 128.0f) + 1e-6f);
;             y = y * rs2 * g2[i];
;             u32x2 wy; wy.x = cvt_pk_bf16(y[0], y[1]); wy.y = cvt_pk_bf16(y[2], y[3]);
;             *(u32x2*)(mixed + pg8::tiled_off(t, 1024 + col, DM / 64)) = wy;
	v_add_f32_e32 v40, v40, v41
	ds_bpermute_b32 v41, v197, v40
	v_mov_b64_e32 v[182:183], v[90:91]
	v_mov_b64_e32 v[168:169], v[116:117]
	v_mov_b64_e32 v[144:145], v[130:131]
	v_mov_b64_e32 v[170:171], v[114:115]
	s_waitcnt lgkmcnt(0)
	v_add_f32_e32 v40, v40, v41
	ds_bpermute_b32 v41, v198, v40
	v_mov_b64_e32 v[172:173], v[112:113]
	v_mov_b64_e32 v[174:175], v[110:111]
	v_mov_b64_e32 v[176:177], v[108:109]
	v_mov_b64_e32 v[178:179], v[106:107]
	s_waitcnt lgkmcnt(0)
	v_add_f32_e32 v40, v40, v41
	v_mov_b64_e32 v[180:181], v[76:77]
	v_mov_b64_e32 v[164:165], v[104:105]
	s_nop 1
	v_add_f32_dpp v40, v40, v40 quad_perm:[2,3,0,1] row_mask:0xf bank_mask:0xf
	s_nop 1
	v_add_f32_dpp v40, v40, v40 quad_perm:[1,0,3,2] row_mask:0xf bank_mask:0xf
	v_fmamk_f32 v40, v40, 0x3c000000, v224
	v_cmp_gt_f32_e32 vcc, s0, v40
	v_mul_f32_e32 v41, 0x4b800000, v40
	s_nop 0
	v_cndmask_b32_e32 v40, v40, v41, vcc
	v_rsq_f32_e32 v40, v40
	s_nop 0
	v_mul_f32_e32 v41, 0x45800000, v40
	v_cndmask_b32_e32 v40, v40, v41, vcc
	v_pk_mul_f32 v[36:37], v[36:37], v[40:41] op_sel_hi:[1,0]
	v_pk_mul_f32 v[38:39], v[38:39], v[40:41] op_sel_hi:[1,0]
	v_pk_mul_f32 v[32:33], v[32:33], v[36:37]
	v_pk_mul_f32 v[34:35], v[34:35], v[38:39]
	v_cvt_pk_bf16_f32 v32, v32, v33
	v_lshlrev_b32_e32 v36, 16, v157
	v_cvt_pk_bf16_f32 v33, v34, v35
	v_or_b32_e32 v34, v207, v202
	v_ashrrev_i32_e32 v35, 31, v34
	v_lshlrev_b64 v[34:35], 14, v[34:35]
	v_lshl_add_u64 v[34:35], v[166:167], 0, v[34:35]
	global_store_dwordx2 v[34:35], v[32:33], off
	v_lshlrev_b32_e32 v32, 16, v158
	v_and_b32_e32 v33, 0xffff0000, v158
	v_lshlrev_b32_e32 v34, 16, v156
	v_and_b32_e32 v35, 0xffff0000, v156
	v_pk_mul_f32 v[32:33], v[34:35], v[32:33]
	v_lshlrev_b32_e32 v34, 16, v159
	v_and_b32_e32 v35, 0xffff0000, v159
	v_and_b32_e32 v37, 0xffff0000, v157
	v_pk_mul_f32 v[34:35], v[36:37], v[34:35]
	v_lshlrev_b32_e32 v36, 16, v150
	v_and_b32_e32 v37, 0xffff0000, v150
	v_lshlrev_b32_e32 v38, 16, v146
	v_and_b32_e32 v39, 0xffff0000, v146
	v_pk_mul_f32 v[36:37], v[38:39], v[36:37]
	v_lshlrev_b32_e32 v38, 16, v151
	v_and_b32_e32 v39, 0xffff0000, v151
	v_lshlrev_b32_e32 v40, 16, v147
	v_and_b32_e32 v41, 0xffff0000, v147
	v_pk_mul_f32 v[38:39], v[40:41], v[38:39]
	v_lshlrev_b32_e32 v40, 16, v148
	v_and_b32_e32 v41, 0xffff0000, v148
	v_pk_mul_f32 v[40:41], v[42:43], v[40:41]
	v_lshlrev_b32_e32 v42, 16, v149
	v_and_b32_e32 v43, 0xffff0000, v149
	v_pk_mul_f32 v[42:43], v[44:45], v[42:43]
	v_pk_mul_f32 v[30:31], v[38:39], v[30:31]
	v_pk_mul_f32 v[28:29], v[36:37], v[28:29]
	v_pk_fma_f32 v[22:23], v[42:43], v[22:23], v[30:31]
	v_pk_fma_f32 v[20:21], v[40:41], v[20:21], v[28:29]
	v_lshlrev_b32_e32 v44, 16, v142
	v_and_b32_e32 v45, 0xffff0000, v142
	v_pk_fma_f32 v[22:23], v[34:35], v[26:27], v[22:23]
	v_pk_fma_f32 v[20:21], v[32:33], v[24:25], v[20:21]
	v_pk_mul_f32 v[22:23], v[22:23], v[46:47]
	v_pk_mul_f32 v[20:21], v[20:21], v[44:45]
	v_pk_mul_f32 v[24:25], v[22:23], v[22:23]
	v_pk_mul_f32 v[26:27], v[20:21], v[20:21]
	v_lshlrev_b32_e32 v30, 16, v83
	v_pk_mov_b32 v[28:29], v[26:27], v[24:25] op_sel:[1,0]
	v_mov_b32_e32 v27, v25
	v_pk_add_f32 v[24:25], v[28:29], v[26:27]
	v_lshlrev_b32_e32 v26, 16, v96
	v_add_f32_e32 v24, v24, v25
	ds_bpermute_b32 v25, v196, v24
	v_and_b32_e32 v27, 0xffff0000, v96
	v_lshlrev_b32_e32 v28, 16, v97
	v_and_b32_e32 v29, 0xffff0000, v97
	v_and_b32_e32 v31, 0xffff0000, v83
	s_waitcnt lgkmcnt(0)
	v_add_f32_e32 v24, v24, v25
	ds_bpermute_b32 v25, v197, v24
	v_mov_b64_e32 v[148:149], v[128:129]
	v_mov_b64_e32 v[146:147], v[126:127]
	v_mov_b64_e32 v[150:151], v[124:125]
	v_mov_b64_e32 v[156:157], v[122:123]
	s_waitcnt lgkmcnt(0)
	v_add_f32_e32 v24, v24, v25
	ds_bpermute_b32 v25, v198, v24
	v_mov_b64_e32 v[158:159], v[120:121]
	v_mov_b64_e32 v[142:143], v[118:119]
	v_mov_b32_e32 v96, v162
	v_mov_b32_e32 v97, v163
	s_waitcnt lgkmcnt(0)
; __device__ __forceinline__ unsigned cvt_pk_bf16(float lo, float hi) { unsigned r; asm volatile("v_cvt_pk_bf16_f32 %0, %1, %2" : "=v"(r) : "v"(lo), "v"(hi)); return r; }
; __device__ __forceinline__ float bflo(unsigned w) { return __uint_as_float(w << 16); }
; __device__ __forceinline__ float bfhi(unsigned w) { return __uint_as_float(w & 0xffff0000u); }
; __device__ __forceinline__ void conv_phase(const Params& p, int l, int rbase) {
;     ...
;         for (int i = 0; i < 4; ++i) { const int col = i * 256 + lane * 4;
;             cw0[i] = *(const f32x4*)(cw + col); cw1[i] = *(const f32x4*)(cw + 1024 + col); cw2[i] = *(const f32x4*)(cw + 2048 + col); g2[i] = *(const f32x4*)(gain + 1024 + col); }
; #pragma unroll
;         for (int i = 0; i < 4; ++i) {
;             const int col = i * 256 + lane * 4;
;             f32x4 c0, c1, c2, gbv;
;             c0[0] = bflo(gc0[i].x) * bflo(hi0[i].x); c0[1] = bfhi(gc0[i].x) * bfhi(hi0[i].x); c0[2] = bflo(gc0[i].y) * bflo(hi0[i].y); c0[3] = bfhi(gc0[i].y) * bfhi(hi0[i].y);
;             c1[0] = bflo(gc1[i].x) * bflo(hi1[i].x); c1[1] = bfhi(gc1[i].x) * bfhi(hi1[i].x); c1[2] = bflo(gc1[i].y) * bflo(hi1[i].y); c1[3] = bfhi(gc1[i].y) * bfhi(hi1[i].y);
;             c2[0] = bflo(gc2[i].x) * bflo(hi2[i].x); c2[1] = bfhi(gc2[i].x) * bfhi(hi2[i].x); c2[2] = bflo(gc2[i].y) * bflo(hi2[i].y); c2[3] = bfhi(gc2[i].y) * bfhi(hi2[i].y);
;             gbv[0] = bflo(gb[i].x); gbv[1] = bfhi(gb[i].x); gbv[2] = bflo(gb[i].y); gbv[3] = bfhi(gb[i].y);
;             f32x4 y = gbv * (cw0[i] * c2 + cw1[i] * c1 + cw2[i] * c0);
;             float s2 = (y[0] * y[0] + y[1] * y[1]) + (y[2] * y[2] + y[3] * y[3]);
; #pragma unroll
;             for (int sft = 16; sft >= 1; sft >>= 1) s2 += __shfl_xor(s2, sft);
;             const float rs2 = rsqrtf(s2 * (1.0f / 128.0f) + 1e-6f);
;             y = y * rs2 * g2[i];
;             u32x2 wy; wy.x = cvt_pk_bf16(y[0], y[1]); wy.y = cvt_pk_bf16(y[2], y[3]);
;             *(u32x2*)(mixed + pg8::tiled_off(t, 1024 + col, DM / 64)) = wy;
;         }
;     }
	v_add_f32_e32 v24, v24, v25
	s_nop 1
	v_add_f32_dpp v24, v24, v24 quad_perm:[2,3,0,1] row_mask:0xf bank_mask:0xf
	s_nop 1
	v_add_f32_dpp v24, v24, v24 quad_perm:[1,0,3,2] row_mask:0xf bank_mask:0xf
	v_fmamk_f32 v24, v24, 0x3c000000, v224
	v_cmp_gt_f32_e32 vcc, s0, v24
	v_mul_f32_e32 v25, 0x4b800000, v24
	s_nop 0
	v_cndmask_b32_e32 v24, v24, v25, vcc
	v_rsq_f32_e32 v24, v24
	s_nop 0
	v_mul_f32_e32 v25, 0x45800000, v24
	v_cndmask_b32_e32 v24, v24, v25, vcc
	v_pk_mul_f32 v[20:21], v[20:21], v[24:25] op_sel_hi:[1,0]
	v_pk_mul_f32 v[22:23], v[22:23], v[24:25] op_sel_hi:[1,0]
	v_pk_mul_f32 v[16:17], v[16:17], v[20:21]
	v_pk_mul_f32 v[18:19], v[18:19], v[22:23]
	v_cvt_pk_bf16_f32 v16, v16, v17
	v_lshlrev_b32_e32 v20, 16, v95
	v_cvt_pk_bf16_f32 v17, v18, v19
	v_or_b32_e32 v18, v207, v203
	v_ashrrev_i32_e32 v19, 31, v18
	v_lshlrev_b64 v[18:19], 14, v[18:19]
	v_lshl_add_u64 v[18:19], v[166:167], 0, v[18:19]
	global_store_dwordx2 v[18:19], v[16:17], off
	v_lshlrev_b32_e32 v16, 16, v100
	v_and_b32_e32 v17, 0xffff0000, v100
	v_lshlrev_b32_e32 v18, 16, v94
	v_and_b32_e32 v19, 0xffff0000, v94
	v_pk_mul_f32 v[16:17], v[18:19], v[16:17]
	v_lshlrev_b32_e32 v18, 16, v101
	v_and_b32_e32 v19, 0xffff0000, v101
	v_and_b32_e32 v21, 0xffff0000, v95
	v_pk_mul_f32 v[18:19], v[20:21], v[18:19]
	v_lshlrev_b32_e32 v20, 16, v92
	v_and_b32_e32 v21, 0xffff0000, v92
	v_lshlrev_b32_e32 v22, 16, v88
	v_and_b32_e32 v23, 0xffff0000, v88
	v_pk_mul_f32 v[20:21], v[22:23], v[20:21]
	v_lshlrev_b32_e32 v22, 16, v93
	v_and_b32_e32 v23, 0xffff0000, v93
	v_lshlrev_b32_e32 v24, 16, v89
	v_and_b32_e32 v25, 0xffff0000, v89
	v_pk_mul_f32 v[22:23], v[24:25], v[22:23]
	v_lshlrev_b32_e32 v24, 16, v102
	v_and_b32_e32 v25, 0xffff0000, v102
	v_pk_mul_f32 v[24:25], v[26:27], v[24:25]
	v_lshlrev_b32_e32 v26, 16, v103
	v_and_b32_e32 v27, 0xffff0000, v103
	v_pk_mul_f32 v[26:27], v[28:29], v[26:27]
	v_pk_mul_f32 v[14:15], v[22:23], v[14:15]
	v_pk_mul_f32 v[12:13], v[20:21], v[12:13]
	v_pk_fma_f32 v[10:11], v[26:27], v[10:11], v[14:15]
	v_pk_fma_f32 v[8:9], v[24:25], v[8:9], v[12:13]
	v_lshlrev_b32_e32 v28, 16, v82
	v_and_b32_e32 v29, 0xffff0000, v82
	v_pk_fma_f32 v[6:7], v[18:19], v[6:7], v[10:11]
	v_pk_fma_f32 v[4:5], v[16:17], v[4:5], v[8:9]
	v_pk_mul_f32 v[6:7], v[6:7], v[30:31]
	v_pk_mul_f32 v[4:5], v[4:5], v[28:29]
	v_pk_mul_f32 v[8:9], v[6:7], v[6:7]
	v_pk_mul_f32 v[10:11], v[4:5], v[4:5]
	v_mov_b64_e32 v[88:89], v[140:141]
	v_pk_mov_b32 v[12:13], v[10:11], v[8:9] op_sel:[1,0]
	v_mov_b32_e32 v11, v9
	v_pk_add_f32 v[8:9], v[12:13], v[10:11]
	v_mov_b64_e32 v[92:93], v[138:139]
	v_add_f32_e32 v8, v8, v9
	ds_bpermute_b32 v9, v196, v8
	v_mov_b64_e32 v[94:95], v[136:137]
	v_mov_b64_e32 v[100:101], v[134:135]
	v_mov_b64_e32 v[82:83], v[132:133]
	v_mov_b32_e32 v102, v160
	s_waitcnt lgkmcnt(0)
	v_add_f32_e32 v8, v8, v9
	ds_bpermute_b32 v9, v197, v8
	v_mov_b32_e32 v103, v161
	s_waitcnt lgkmcnt(0)
	v_add_f32_e32 v8, v8, v9
	ds_bpermute_b32 v9, v198, v8
	s_waitcnt lgkmcnt(0)
	v_add_f32_e32 v8, v8, v9
	s_nop 1
	v_add_f32_dpp v8, v8, v8 quad_perm:[2,3,0,1] row_mask:0xf bank_mask:0xf
	s_nop 1
	v_add_f32_dpp v8, v8, v8 quad_perm:[1,0,3,2] row_mask:0xf bank_mask:0xf
	v_fmamk_f32 v8, v8, 0x3c000000, v224
	v_cmp_gt_f32_e32 vcc, s0, v8
	v_mul_f32_e32 v9, 0x4b800000, v8
	s_nop 0
	v_cndmask_b32_e32 v8, v8, v9, vcc
	v_rsq_f32_e32 v8, v8
	s_nop 0
	v_mul_f32_e32 v9, 0x45800000, v8
	v_cndmask_b32_e32 v8, v8, v9, vcc
	v_pk_mul_f32 v[4:5], v[4:5], v[8:9] op_sel_hi:[1,0]
	v_pk_mul_f32 v[6:7], v[6:7], v[8:9] op_sel_hi:[1,0]
	v_pk_mul_f32 v[0:1], v[0:1], v[4:5]
	v_pk_mul_f32 v[2:3], v[2:3], v[6:7]
	v_cvt_pk_bf16_f32 v0, v0, v1
	s_nop 0
	v_cvt_pk_bf16_f32 v1, v2, v3
	v_or_b32_e32 v2, v207, v204
	v_ashrrev_i32_e32 v3, 31, v2
	v_lshlrev_b64 v[2:3], 14, v[2:3]
	v_lshl_add_u64 v[2:3], v[166:167], 0, v[2:3]
	v_mov_b32_e32 v166, v206
	global_store_dwordx2 v[2:3], v[0:1], off
	s_andn2_b64 exec, exec, s[8:9]
	s_cbranch_execz .LBB0_294
